# K-loop: all 16 LDS-DMA issues use SGPR-base + VGPR-offset form; bases stepped on SALU, k+1 tiles via offset:128 with M0-128
# baseline (speedup 1.0000x reference)
.LBB0_386:
	s_add_i32 s71, s44, 2
	s_add_u32 s46, s0, 0x80
	s_addc_u32 s45, s1, 0
	s_add_i32 vcc_lo, 0, 0x10000
	s_cmp_eq_u32 s43, s44
	s_cselect_b32 s44, s72, s46
	s_cselect_b32 s45, s73, s45
	s_cselect_b32 s47, s75, s49
	s_cselect_b32 s46, s74, s48
	s_nop 0
	s_add_i32 m0, s98, 0xc000
	ds_read_b128 v[146:149], v229
	ds_read_b128 v[150:153], v229 offset:1024
	ds_read_b128 v[176:179], v229 offset:2048
	ds_read_b128 v[180:183], v229 offset:3072
	ds_read_b128 v[184:187], v229 offset:4096
	ds_read_b128 v[188:191], v229 offset:5120
	ds_read_b128 v[192:195], v229 offset:6144
	ds_read_b128 v[196:199], v229 offset:7168
	global_load_lds_dwordx4 v172, s[0:1]
	s_add_i32 m0, s98, 0xe000
	s_nop 0
	global_load_lds_dwordx4 v174, s[0:1]
	s_waitcnt lgkmcnt(8)
	s_barrier
	s_waitcnt lgkmcnt(0)
	v_mfma_f32_16x16x32_bf16 v[126:129], v[130:133], v[146:149], v[126:129]
	v_mfma_f32_16x16x32_bf16 v[122:125], v[138:141], v[146:149], v[122:125]
	v_mfma_f32_16x16x32_bf16 v[110:113], v[130:133], v[176:179], v[110:113]
	v_mfma_f32_16x16x32_bf16 v[106:109], v[138:141], v[176:179], v[106:109]
	v_mfma_f32_16x16x32_bf16 v[94:97], v[130:133], v[184:187], v[94:97]
	v_mfma_f32_16x16x32_bf16 v[90:93], v[138:141], v[184:187], v[90:93]
	v_mfma_f32_16x16x32_bf16 v[78:81], v[130:133], v[192:195], v[78:81]
	v_mfma_f32_16x16x32_bf16 v[74:77], v[138:141], v[192:195], v[74:77]
	v_mfma_f32_16x16x32_bf16 v[126:129], v[134:137], v[150:153], v[126:129]
	v_mfma_f32_16x16x32_bf16 v[122:125], v[142:145], v[150:153], v[122:125]
	v_mfma_f32_16x16x32_bf16 v[110:113], v[134:137], v[180:183], v[110:113]
	v_mfma_f32_16x16x32_bf16 v[106:109], v[142:145], v[180:183], v[106:109]
	v_mfma_f32_16x16x32_bf16 v[94:97], v[134:137], v[188:191], v[94:97]
	v_mfma_f32_16x16x32_bf16 v[90:93], v[142:145], v[188:191], v[90:93]
	v_mfma_f32_16x16x32_bf16 v[78:81], v[134:137], v[196:199], v[78:81]
	v_mfma_f32_16x16x32_bf16 v[74:77], v[142:145], v[196:199], v[74:77]
	s_barrier
	s_add_i32 vcc_hi, 0, 0x14000
	s_add_i32 vcc_lo, vcc_lo, s97
	v_add_u32_e32 v0, vcc_hi, v224
	s_mov_b32 m0, vcc_lo
	ds_read_b128 v[200:203], v0
	ds_read_b128 v[230:233], v0 offset:1024
	ds_read_b128 v[234:237], v0 offset:2048
	ds_read_b128 v[238:241], v0 offset:3072
	global_load_lds_dwordx4 v158, s[46:47]
	s_add_i32 m0, vcc_lo, 0x2000
	s_nop 0
	global_load_lds_dwordx4 v162, s[46:47]
	s_waitcnt vmcnt(6)
	s_barrier
	s_waitcnt lgkmcnt(0)
	v_mfma_f32_16x16x32_bf16 v[118:121], v[200:203], v[146:149], v[118:121]
	v_mfma_f32_16x16x32_bf16 v[114:117], v[234:237], v[146:149], v[114:117]
	v_mfma_f32_16x16x32_bf16 v[102:105], v[200:203], v[176:179], v[102:105]
	v_mfma_f32_16x16x32_bf16 v[98:101], v[234:237], v[176:179], v[98:101]
	v_mfma_f32_16x16x32_bf16 v[86:89], v[200:203], v[184:187], v[86:89]
	v_mfma_f32_16x16x32_bf16 v[82:85], v[234:237], v[184:187], v[82:85]
	v_mfma_f32_16x16x32_bf16 v[70:73], v[200:203], v[192:195], v[70:73]
	v_mfma_f32_16x16x32_bf16 v[66:69], v[234:237], v[192:195], v[66:69]
	v_mfma_f32_16x16x32_bf16 v[118:121], v[230:233], v[150:153], v[118:121]
	v_mfma_f32_16x16x32_bf16 v[114:117], v[238:241], v[150:153], v[114:117]
	v_mfma_f32_16x16x32_bf16 v[102:105], v[230:233], v[180:183], v[102:105]
	v_mfma_f32_16x16x32_bf16 v[98:101], v[238:241], v[180:183], v[98:101]
	v_mfma_f32_16x16x32_bf16 v[86:89], v[230:233], v[188:191], v[86:89]
	v_mfma_f32_16x16x32_bf16 v[82:85], v[238:241], v[188:191], v[82:85]
	v_mfma_f32_16x16x32_bf16 v[70:73], v[230:233], v[196:199], v[70:73]
	v_mfma_f32_16x16x32_bf16 v[66:69], v[238:241], v[196:199], v[66:69]
	s_barrier
	s_mov_b32 m0, s98
	ds_read_b128 v[146:149], v229 offset:16384
	ds_read_b128 v[150:153], v229 offset:17408
	ds_read_b128 v[176:179], v229 offset:18432
	ds_read_b128 v[180:183], v229 offset:19456
	ds_read_b128 v[184:187], v229 offset:20480
	ds_read_b128 v[188:191], v229 offset:21504
	ds_read_b128 v[192:195], v229 offset:22528
	ds_read_b128 v[196:199], v229 offset:23552
	global_load_lds_dwordx4 v156, s[44:45]
	s_mov_b32 m0, s99
	s_nop 0
	global_load_lds_dwordx4 v160, s[44:45]
	s_barrier
	s_waitcnt lgkmcnt(0)
	v_mfma_f32_16x16x32_bf16 v[62:65], v[130:133], v[146:149], v[62:65]
	v_mfma_f32_16x16x32_bf16 v[58:61], v[138:141], v[146:149], v[58:61]
	v_mfma_f32_16x16x32_bf16 v[46:49], v[130:133], v[176:179], v[46:49]
	v_mfma_f32_16x16x32_bf16 v[42:45], v[138:141], v[176:179], v[42:45]
	v_mfma_f32_16x16x32_bf16 v[30:33], v[130:133], v[184:187], v[30:33]
	v_mfma_f32_16x16x32_bf16 v[26:29], v[138:141], v[184:187], v[26:29]
	v_mfma_f32_16x16x32_bf16 v[14:17], v[130:133], v[192:195], v[14:17]
	v_mfma_f32_16x16x32_bf16 v[10:13], v[138:141], v[192:195], v[10:13]
	v_mfma_f32_16x16x32_bf16 v[62:65], v[134:137], v[150:153], v[62:65]
	v_mfma_f32_16x16x32_bf16 v[58:61], v[142:145], v[150:153], v[58:61]
	v_mfma_f32_16x16x32_bf16 v[46:49], v[134:137], v[180:183], v[46:49]
	v_mfma_f32_16x16x32_bf16 v[42:45], v[142:145], v[180:183], v[42:45]
	v_mfma_f32_16x16x32_bf16 v[30:33], v[134:137], v[188:191], v[30:33]
	v_mfma_f32_16x16x32_bf16 v[26:29], v[142:145], v[188:191], v[26:29]
	v_mfma_f32_16x16x32_bf16 v[14:17], v[134:137], v[196:199], v[14:17]
	v_mfma_f32_16x16x32_bf16 v[10:13], v[142:145], v[196:199], v[10:13]
	s_barrier
	s_add_i32 vcc_lo, vcc_hi, s97
	s_mov_b32 m0, vcc_lo
	s_add_u32 s46, s46, s95
	s_addc_u32 s47, s47, 0
	global_load_lds_dwordx4 v158, s[46:47]
	s_add_i32 m0, vcc_lo, 0x2000
	s_nop 0
	global_load_lds_dwordx4 v162, s[46:47]
	v_add_u32_e32 v0, 0x18000, v224
	ds_read_b128 v[130:133], v0
	ds_read_b128 v[134:137], v0 offset:1024
	ds_read_b128 v[138:141], v0 offset:2048
	ds_read_b128 v[142:145], v0 offset:3072
	s_waitcnt vmcnt(6)
	s_barrier
	v_mfma_f32_16x16x32_bf16 v[54:57], v[200:203], v[146:149], v[54:57]
	v_mfma_f32_16x16x32_bf16 v[50:53], v[234:237], v[146:149], v[50:53]
	v_mfma_f32_16x16x32_bf16 v[38:41], v[200:203], v[176:179], v[38:41]
	v_mfma_f32_16x16x32_bf16 v[34:37], v[234:237], v[176:179], v[34:37]
	v_mfma_f32_16x16x32_bf16 v[22:25], v[200:203], v[184:187], v[22:25]
	v_mfma_f32_16x16x32_bf16 v[18:21], v[234:237], v[184:187], v[18:21]
	v_mfma_f32_16x16x32_bf16 v[6:9], v[200:203], v[192:195], v[6:9]
	v_mfma_f32_16x16x32_bf16 v[2:5], v[234:237], v[192:195], v[2:5]
	v_mfma_f32_16x16x32_bf16 v[54:57], v[230:233], v[150:153], v[54:57]
	v_mfma_f32_16x16x32_bf16 v[50:53], v[238:241], v[150:153], v[50:53]
	v_mfma_f32_16x16x32_bf16 v[38:41], v[230:233], v[180:183], v[38:41]
	v_mfma_f32_16x16x32_bf16 v[34:37], v[238:241], v[180:183], v[34:37]
	v_mfma_f32_16x16x32_bf16 v[22:25], v[230:233], v[188:191], v[22:25]
	v_mfma_f32_16x16x32_bf16 v[18:21], v[238:241], v[188:191], v[18:21]
	v_mfma_f32_16x16x32_bf16 v[6:9], v[230:233], v[196:199], v[6:9]
	v_mfma_f32_16x16x32_bf16 v[2:5], v[238:241], v[196:199], v[2:5]
	s_barrier
	s_add_u32 s44, s44, s20
	s_addc_u32 s45, s45, 0
	s_mov_b32 m0, s94
	ds_read_b128 v[146:149], v229 offset:32768
	ds_read_b128 v[150:153], v229 offset:33792
	ds_read_b128 v[176:179], v229 offset:34816
	ds_read_b128 v[180:183], v229 offset:35840
	ds_read_b128 v[184:187], v229 offset:36864
	ds_read_b128 v[188:191], v229 offset:37888
	ds_read_b128 v[192:195], v229 offset:38912
	ds_read_b128 v[196:199], v229 offset:39936
	global_load_lds_dwordx4 v156, s[44:45]
	s_mov_b32 m0, s65
	s_nop 0
	global_load_lds_dwordx4 v160, s[44:45]
	s_waitcnt lgkmcnt(8)
	s_barrier
	s_waitcnt lgkmcnt(0)
	v_mfma_f32_16x16x32_bf16 v[126:129], v[130:133], v[146:149], v[126:129]
	v_mfma_f32_16x16x32_bf16 v[122:125], v[138:141], v[146:149], v[122:125]
	v_mfma_f32_16x16x32_bf16 v[110:113], v[130:133], v[176:179], v[110:113]
	v_mfma_f32_16x16x32_bf16 v[106:109], v[138:141], v[176:179], v[106:109]
	v_mfma_f32_16x16x32_bf16 v[94:97], v[130:133], v[184:187], v[94:97]
	v_mfma_f32_16x16x32_bf16 v[90:93], v[138:141], v[184:187], v[90:93]
	v_mfma_f32_16x16x32_bf16 v[78:81], v[130:133], v[192:195], v[78:81]
	v_mfma_f32_16x16x32_bf16 v[74:77], v[138:141], v[192:195], v[74:77]
	v_mfma_f32_16x16x32_bf16 v[126:129], v[134:137], v[150:153], v[126:129]
	v_mfma_f32_16x16x32_bf16 v[122:125], v[142:145], v[150:153], v[122:125]
	v_mfma_f32_16x16x32_bf16 v[110:113], v[134:137], v[180:183], v[110:113]
	v_mfma_f32_16x16x32_bf16 v[106:109], v[142:145], v[180:183], v[106:109]
	v_mfma_f32_16x16x32_bf16 v[94:97], v[134:137], v[188:191], v[94:97]
	v_mfma_f32_16x16x32_bf16 v[90:93], v[142:145], v[188:191], v[90:93]
	v_mfma_f32_16x16x32_bf16 v[78:81], v[134:137], v[196:199], v[78:81]
	v_mfma_f32_16x16x32_bf16 v[74:77], v[142:145], v[196:199], v[74:77]
	s_barrier
	s_sub_u32 s46, s46, s95
	s_subb_u32 s47, s47, 0
	s_add_i32 vcc_lo, s97, 0x17f80
	v_add_u32_e32 v0, 0x1c000, v224
	s_mov_b32 m0, vcc_lo
	ds_read_b128 v[200:203], v0
	ds_read_b128 v[230:233], v0 offset:1024
	ds_read_b128 v[234:237], v0 offset:2048
	ds_read_b128 v[238:241], v0 offset:3072
	global_load_lds_dwordx4 v158, s[46:47] offset:128
	s_add_i32 m0, vcc_lo, 0x2000
	s_nop 0
	global_load_lds_dwordx4 v162, s[46:47] offset:128
	s_waitcnt vmcnt(6)
	s_barrier
	s_waitcnt lgkmcnt(0)
	v_mfma_f32_16x16x32_bf16 v[118:121], v[200:203], v[146:149], v[118:121]
	v_mfma_f32_16x16x32_bf16 v[114:117], v[234:237], v[146:149], v[114:117]
	v_mfma_f32_16x16x32_bf16 v[102:105], v[200:203], v[176:179], v[102:105]
	v_mfma_f32_16x16x32_bf16 v[98:101], v[234:237], v[176:179], v[98:101]
	v_mfma_f32_16x16x32_bf16 v[86:89], v[200:203], v[184:187], v[86:89]
	v_mfma_f32_16x16x32_bf16 v[82:85], v[234:237], v[184:187], v[82:85]
	v_mfma_f32_16x16x32_bf16 v[70:73], v[200:203], v[192:195], v[70:73]
	v_mfma_f32_16x16x32_bf16 v[66:69], v[234:237], v[192:195], v[66:69]
	v_mfma_f32_16x16x32_bf16 v[118:121], v[230:233], v[150:153], v[118:121]
	v_mfma_f32_16x16x32_bf16 v[114:117], v[238:241], v[150:153], v[114:117]
	v_mfma_f32_16x16x32_bf16 v[102:105], v[230:233], v[180:183], v[102:105]
	v_mfma_f32_16x16x32_bf16 v[98:101], v[238:241], v[180:183], v[98:101]
	v_mfma_f32_16x16x32_bf16 v[86:89], v[230:233], v[188:191], v[86:89]
	v_mfma_f32_16x16x32_bf16 v[82:85], v[238:241], v[188:191], v[82:85]
	v_mfma_f32_16x16x32_bf16 v[70:73], v[230:233], v[196:199], v[70:73]
	v_mfma_f32_16x16x32_bf16 v[66:69], v[238:241], v[196:199], v[66:69]
	s_barrier
	s_sub_u32 s44, s44, s20
	s_subb_u32 s45, s45, 0
	s_add_i32 m0, s87, 0xffffff80
	ds_read_b128 v[146:149], v229 offset:49152
	ds_read_b128 v[150:153], v229 offset:50176
	ds_read_b128 v[176:179], v229 offset:51200
	ds_read_b128 v[180:183], v229 offset:52224
	ds_read_b128 v[184:187], v229 offset:53248
	ds_read_b128 v[188:191], v229 offset:54272
	ds_read_b128 v[192:195], v229 offset:55296
	ds_read_b128 v[196:199], v229 offset:56320
	global_load_lds_dwordx4 v156, s[44:45] offset:128
	s_add_i32 m0, s29, 0xffffff80
	s_nop 0
	global_load_lds_dwordx4 v160, s[44:45] offset:128
	s_barrier
	s_waitcnt lgkmcnt(0)
	v_mfma_f32_16x16x32_bf16 v[62:65], v[130:133], v[146:149], v[62:65]
	v_mfma_f32_16x16x32_bf16 v[58:61], v[138:141], v[146:149], v[58:61]
	v_mfma_f32_16x16x32_bf16 v[46:49], v[130:133], v[176:179], v[46:49]
	v_mfma_f32_16x16x32_bf16 v[42:45], v[138:141], v[176:179], v[42:45]
	v_mfma_f32_16x16x32_bf16 v[30:33], v[130:133], v[184:187], v[30:33]
	v_mfma_f32_16x16x32_bf16 v[26:29], v[138:141], v[184:187], v[26:29]
	v_mfma_f32_16x16x32_bf16 v[14:17], v[130:133], v[192:195], v[14:17]
	v_mfma_f32_16x16x32_bf16 v[10:13], v[138:141], v[192:195], v[10:13]
	v_mfma_f32_16x16x32_bf16 v[62:65], v[134:137], v[150:153], v[62:65]
	v_mfma_f32_16x16x32_bf16 v[58:61], v[142:145], v[150:153], v[58:61]
	v_mfma_f32_16x16x32_bf16 v[46:49], v[134:137], v[180:183], v[46:49]
	v_mfma_f32_16x16x32_bf16 v[42:45], v[142:145], v[180:183], v[42:45]
	v_mfma_f32_16x16x32_bf16 v[30:33], v[134:137], v[188:191], v[30:33]
	v_mfma_f32_16x16x32_bf16 v[26:29], v[142:145], v[188:191], v[26:29]
	v_mfma_f32_16x16x32_bf16 v[14:17], v[134:137], v[196:199], v[14:17]
	v_mfma_f32_16x16x32_bf16 v[10:13], v[142:145], v[196:199], v[10:13]
	s_barrier
	s_add_i32 vcc_lo, s97, 0x1bf80
	s_mov_b32 m0, vcc_lo
	s_add_u32 s46, s46, s95
	s_addc_u32 s47, s47, 0
	global_load_lds_dwordx4 v158, s[46:47] offset:128
	s_add_i32 m0, vcc_lo, 0x2000
	s_nop 0
	global_load_lds_dwordx4 v162, s[46:47] offset:128
	v_add_u32_e32 v0, 0x10000, v224
	ds_read_b128 v[130:133], v0
	ds_read_b128 v[134:137], v0 offset:1024
	ds_read_b128 v[138:141], v0 offset:2048
	ds_read_b128 v[142:145], v0 offset:3072
	s_add_u32 s0, s0, 0x100
	s_addc_u32 s1, s1, 0
	s_add_u32 s48, s48, 0x100
	s_addc_u32 s49, s49, 0
	s_cmp_ge_i32 s71, s6
	s_mov_b32 s44, s71
	s_waitcnt vmcnt(6)
	s_barrier
	v_mfma_f32_16x16x32_bf16 v[54:57], v[200:203], v[146:149], v[54:57]
	v_mfma_f32_16x16x32_bf16 v[50:53], v[234:237], v[146:149], v[50:53]
	v_mfma_f32_16x16x32_bf16 v[38:41], v[200:203], v[176:179], v[38:41]
	v_mfma_f32_16x16x32_bf16 v[34:37], v[234:237], v[176:179], v[34:37]
	v_mfma_f32_16x16x32_bf16 v[22:25], v[200:203], v[184:187], v[22:25]
	v_mfma_f32_16x16x32_bf16 v[18:21], v[234:237], v[184:187], v[18:21]
	v_mfma_f32_16x16x32_bf16 v[6:9], v[200:203], v[192:195], v[6:9]
	v_mfma_f32_16x16x32_bf16 v[2:5], v[234:237], v[192:195], v[2:5]
	v_mfma_f32_16x16x32_bf16 v[54:57], v[230:233], v[150:153], v[54:57]
	v_mfma_f32_16x16x32_bf16 v[50:53], v[238:241], v[150:153], v[50:53]
	v_mfma_f32_16x16x32_bf16 v[38:41], v[230:233], v[180:183], v[38:41]
	v_mfma_f32_16x16x32_bf16 v[34:37], v[238:241], v[180:183], v[34:37]
	v_mfma_f32_16x16x32_bf16 v[22:25], v[230:233], v[188:191], v[22:25]
	v_mfma_f32_16x16x32_bf16 v[18:21], v[238:241], v[188:191], v[18:21]
	v_mfma_f32_16x16x32_bf16 v[6:9], v[230:233], v[196:199], v[6:9]
	v_mfma_f32_16x16x32_bf16 v[2:5], v[238:241], v[196:199], v[2:5]
	s_barrier
	s_cbranch_scc0 .LBB0_386
	s_lshl_b32 s46, s77, 8
	s_cmp_lt_i32 s64, 1
	s_mov_b64 s[0:1], -1
	s_cbranch_scc1 .LBB0_403
